# grid barrier: the last XCD leader no longer bumps the (now unread) generation word, so it does not wait for that atomic before leaving the barrier
# speedup vs baseline: 1.0075x; 1.0075x over previous
; __device__ __forceinline__ unsigned xb_ld(unsigned* p)              { return __hip_atomic_load(p, __ATOMIC_RELAXED, __HIP_MEMORY_SCOPE_AGENT); }
; __device__ __forceinline__ unsigned xb_add(unsigned* p, unsigned v) { return __hip_atomic_fetch_add(p, v, __ATOMIC_RELAXED, __HIP_MEMORY_SCOPE_AGENT); }
; #define XB_SPIN(cond, bar) do { unsigned _sp = 0; while (cond) { __builtin_amdgcn_s_sleep(1); \
;     if ((++_sp & 255u) == 0u) { if (xb_ld(&(bar)[XB_TMO])) break; if (_sp > XB_SPIN_CAP) { atomicAdd(&(bar)[XB_TMO], 1u); break; } } } } while (0)
; __device__ __forceinline__ void xcd_barrier(const XcdBarrier& b) {
;     ...
;         const unsigned old = xb_add(&bar[XB_XSUB(b.x)], 1u);
;         const unsigned gen = old / nloc;
;         if (old + 1u == (gen + 1u) * nloc) {
;             __builtin_amdgcn_fence(__ATOMIC_RELEASE, "agent");
;             asm volatile("s_waitcnt vmcnt(0)" ::: "memory");
;             const unsigned og = xb_add(&bar[XB_TOP], 1u);
;             const unsigned tg = og / nx;
;             if (og + 1u == (tg + 1u) * nx) xb_add(&bar[XB_TOPGEN], 1u);
;             else XB_SPIN(xb_ld(&bar[XB_TOPGEN]) == tg, bar);
;             __builtin_amdgcn_fence(__ATOMIC_ACQUIRE, "agent");
;             xb_add(&bar[XB_XGEN(b.x)], 1u);
;             asm volatile("s_waitcnt vmcnt(0)" ::: "memory");
.LBB0_68:
	s_or_b64 exec, exec, s[6:7]
	v_cvt_f32_u32_e32 v4, v1
	s_waitcnt vmcnt(0)
	v_readfirstlane_b32 s2, v3
	s_add_u32 s6, s54, 0x7500
	s_addc_u32 s7, s55, 0
	v_rcp_iflag_f32_e32 v4, v4
	v_add_u32_e32 v2, s2, v2
	v_add_u32_e32 v5, 1, v2
	s_mov_b64 s[12:13], 0
	v_mul_f32_e32 v3, 0x4f7ffffe, v4
	v_cvt_u32_f32_e32 v3, v3
	v_sub_u32_e32 v4, 0, v1
	v_mul_lo_u32 v4, v4, v3
	v_mul_hi_u32 v4, v3, v4
	v_add_u32_e32 v3, v3, v4
	v_mul_hi_u32 v3, v2, v3
	v_mul_lo_u32 v4, v3, v1
	v_sub_u32_e32 v2, v2, v4
	v_add_u32_e32 v6, 1, v3
	v_cmp_ge_u32_e32 vcc, v2, v1
	v_sub_u32_e32 v4, v2, v1
	s_nop 0
	v_cndmask_b32_e32 v3, v3, v6, vcc
	v_cndmask_b32_e32 v2, v2, v4, vcc
	v_add_u32_e32 v4, 1, v3
	v_cmp_ge_u32_e32 vcc, v2, v1
	s_nop 1
	v_cndmask_b32_e32 v4, v3, v4, vcc
	v_mul_lo_u32 v2, v1, v4
	v_add_u32_e32 v1, v2, v1
	v_mov_b32_e32 v253, v1
	v_cmp_ne_u32_e32 vcc, v5, v1
	v_mov_b64_e32 v[2:3], s[6:7]
	s_and_saveexec_b64 s[2:3], vcc
	s_cbranch_execz .LBB0_80
	v_mov_b32_e32 v1, 0
	global_load_dword v2, v1, s[6:7] offset:-256 sc1
	s_mov_b64 s[16:17], 0
	s_waitcnt vmcnt(0)
	v_cmp_lt_u32_e32 vcc, v2, v253
	s_and_saveexec_b64 s[14:15], vcc
	s_cbranch_execz .LBB0_79
	s_add_u32 s12, s54, 0x4200
	s_addc_u32 s13, s55, 0
	s_mov_b32 s26, 1
	s_branch .LBB0_72

; __device__ __forceinline__ unsigned xb_ld(unsigned* p)              { return __hip_atomic_load(p, __ATOMIC_RELAXED, __HIP_MEMORY_SCOPE_AGENT); }
; __device__ __forceinline__ unsigned xb_add(unsigned* p, unsigned v) { return __hip_atomic_fetch_add(p, v, __ATOMIC_RELAXED, __HIP_MEMORY_SCOPE_AGENT); }
; #define XB_SPIN(cond, bar) do { unsigned _sp = 0; while (cond) { __builtin_amdgcn_s_sleep(1); \
;     if ((++_sp & 255u) == 0u) { if (xb_ld(&(bar)[XB_TMO])) break; if (_sp > XB_SPIN_CAP) { atomicAdd(&(bar)[XB_TMO], 1u); break; } } } } while (0)
; __device__ __forceinline__ void xcd_barrier(const XcdBarrier& b) {
;     ...
;         const unsigned old = xb_add(&bar[XB_XSUB(b.x)], 1u);
;         const unsigned gen = old / nloc;
;         if (old + 1u == (gen + 1u) * nloc) {
;             __builtin_amdgcn_fence(__ATOMIC_RELEASE, "agent");
;             asm volatile("s_waitcnt vmcnt(0)" ::: "memory");
;             const unsigned og = xb_add(&bar[XB_TOP], 1u);
;             const unsigned tg = og / nx;
;             if (og + 1u == (tg + 1u) * nx) xb_add(&bar[XB_TOPGEN], 1u);
;             else XB_SPIN(xb_ld(&bar[XB_TOPGEN]) == tg, bar);
;             __builtin_amdgcn_fence(__ATOMIC_ACQUIRE, "agent");
;             xb_add(&bar[XB_XGEN(b.x)], 1u);
;             asm volatile("s_waitcnt vmcnt(0)" ::: "memory");
.LBB0_151:
	s_or_b64 exec, exec, s[6:7]
	v_cvt_f32_u32_e32 v4, v1
	s_waitcnt vmcnt(0)
	v_readfirstlane_b32 s2, v3
	s_add_u32 s6, s54, 0x7500
	s_addc_u32 s7, s55, 0
	v_rcp_iflag_f32_e32 v4, v4
	v_add_u32_e32 v2, s2, v2
	v_add_u32_e32 v5, 1, v2
	s_mov_b64 s[10:11], 0
	v_mul_f32_e32 v3, 0x4f7ffffe, v4
	v_cvt_u32_f32_e32 v3, v3
	v_sub_u32_e32 v4, 0, v1
	v_mul_lo_u32 v4, v4, v3
	v_mul_hi_u32 v4, v3, v4
	v_add_u32_e32 v3, v3, v4
	v_mul_hi_u32 v3, v2, v3
	v_mul_lo_u32 v4, v3, v1
	v_sub_u32_e32 v2, v2, v4
	v_add_u32_e32 v6, 1, v3
	v_cmp_ge_u32_e32 vcc, v2, v1
	v_sub_u32_e32 v4, v2, v1
	s_nop 0
	v_cndmask_b32_e32 v3, v3, v6, vcc
	v_cndmask_b32_e32 v2, v2, v4, vcc
	v_add_u32_e32 v4, 1, v3
	v_cmp_ge_u32_e32 vcc, v2, v1
	s_nop 1
	v_cndmask_b32_e32 v4, v3, v4, vcc
	v_mul_lo_u32 v2, v1, v4
	v_add_u32_e32 v1, v2, v1
	v_mov_b32_e32 v253, v1
	v_cmp_ne_u32_e32 vcc, v5, v1
	v_mov_b64_e32 v[2:3], s[6:7]
	s_and_saveexec_b64 s[2:3], vcc
	s_cbranch_execz .LBB0_163
	v_mov_b32_e32 v1, 0
	global_load_dword v2, v1, s[6:7] offset:-256 sc1
	s_mov_b64 s[14:15], 0
	s_waitcnt vmcnt(0)
	v_cmp_lt_u32_e32 vcc, v2, v253
	s_and_saveexec_b64 s[12:13], vcc
	s_cbranch_execz .LBB0_162
	s_add_u32 s10, s54, 0x4200
	s_addc_u32 s11, s55, 0
	s_mov_b32 s26, 1
	s_branch .LBB0_155

; __device__ __forceinline__ unsigned xb_ld(unsigned* p)              { return __hip_atomic_load(p, __ATOMIC_RELAXED, __HIP_MEMORY_SCOPE_AGENT); }
; __device__ __forceinline__ unsigned xb_add(unsigned* p, unsigned v) { return __hip_atomic_fetch_add(p, v, __ATOMIC_RELAXED, __HIP_MEMORY_SCOPE_AGENT); }
; #define XB_SPIN(cond, bar) do { unsigned _sp = 0; while (cond) { __builtin_amdgcn_s_sleep(1); \
;     if ((++_sp & 255u) == 0u) { if (xb_ld(&(bar)[XB_TMO])) break; if (_sp > XB_SPIN_CAP) { atomicAdd(&(bar)[XB_TMO], 1u); break; } } } } while (0)
; __device__ __forceinline__ void xcd_barrier(const XcdBarrier& b) {
;     ...
;         const unsigned old = xb_add(&bar[XB_XSUB(b.x)], 1u);
;         const unsigned gen = old / nloc;
;         if (old + 1u == (gen + 1u) * nloc) {
;             __builtin_amdgcn_fence(__ATOMIC_RELEASE, "agent");
;             asm volatile("s_waitcnt vmcnt(0)" ::: "memory");
;             const unsigned og = xb_add(&bar[XB_TOP], 1u);
;             const unsigned tg = og / nx;
;             if (og + 1u == (tg + 1u) * nx) xb_add(&bar[XB_TOPGEN], 1u);
;             else XB_SPIN(xb_ld(&bar[XB_TOPGEN]) == tg, bar);
;             __builtin_amdgcn_fence(__ATOMIC_ACQUIRE, "agent");
;             xb_add(&bar[XB_XGEN(b.x)], 1u);
;             asm volatile("s_waitcnt vmcnt(0)" ::: "memory");
.LBB0_298:
	s_or_b64 exec, exec, s[6:7]
	v_cvt_f32_u32_e32 v4, v1
	s_waitcnt vmcnt(0)
	v_readfirstlane_b32 s2, v3
	s_add_u32 s6, s54, 0x7500
	s_addc_u32 s7, s55, 0
	v_rcp_iflag_f32_e32 v4, v4
	v_add_u32_e32 v2, s2, v2
	v_add_u32_e32 v5, 1, v2
	s_mov_b64 s[8:9], 0
	v_mul_f32_e32 v3, 0x4f7ffffe, v4
	v_cvt_u32_f32_e32 v3, v3
	v_sub_u32_e32 v4, 0, v1
	v_mul_lo_u32 v4, v4, v3
	v_mul_hi_u32 v4, v3, v4
	v_add_u32_e32 v3, v3, v4
	v_mul_hi_u32 v3, v2, v3
	v_mul_lo_u32 v4, v3, v1
	v_sub_u32_e32 v2, v2, v4
	v_add_u32_e32 v6, 1, v3
	v_cmp_ge_u32_e32 vcc, v2, v1
	v_sub_u32_e32 v4, v2, v1
	s_nop 0
	v_cndmask_b32_e32 v3, v3, v6, vcc
	v_cndmask_b32_e32 v2, v2, v4, vcc
	v_add_u32_e32 v4, 1, v3
	v_cmp_ge_u32_e32 vcc, v2, v1
	s_nop 1
	v_cndmask_b32_e32 v4, v3, v4, vcc
	v_mul_lo_u32 v2, v1, v4
	v_add_u32_e32 v1, v2, v1
	v_mov_b32_e32 v253, v1
	v_cmp_ne_u32_e32 vcc, v5, v1
	v_mov_b64_e32 v[2:3], s[6:7]
	s_and_saveexec_b64 s[2:3], vcc
	s_cbranch_execz .LBB0_310
	v_mov_b32_e32 v1, 0
	global_load_dword v2, v1, s[6:7] offset:-256 sc1
	s_mov_b64 s[12:13], 0
	s_waitcnt vmcnt(0)
	v_cmp_lt_u32_e32 vcc, v2, v253
	s_and_saveexec_b64 s[10:11], vcc
	s_cbranch_execz .LBB0_309
	s_add_u32 s8, s54, 0x4200
	s_addc_u32 s9, s55, 0
	s_mov_b32 s24, 1
	s_branch .LBB0_302

; __device__ __forceinline__ unsigned xb_ld(unsigned* p)              { return __hip_atomic_load(p, __ATOMIC_RELAXED, __HIP_MEMORY_SCOPE_AGENT); }
; __device__ __forceinline__ unsigned xb_add(unsigned* p, unsigned v) { return __hip_atomic_fetch_add(p, v, __ATOMIC_RELAXED, __HIP_MEMORY_SCOPE_AGENT); }
; #define XB_SPIN(cond, bar) do { unsigned _sp = 0; while (cond) { __builtin_amdgcn_s_sleep(1); \
;     if ((++_sp & 255u) == 0u) { if (xb_ld(&(bar)[XB_TMO])) break; if (_sp > XB_SPIN_CAP) { atomicAdd(&(bar)[XB_TMO], 1u); break; } } } } while (0)
; __device__ __forceinline__ void xcd_barrier(const XcdBarrier& b) {
;     ...
;         const unsigned old = xb_add(&bar[XB_XSUB(b.x)], 1u);
;         const unsigned gen = old / nloc;
;         if (old + 1u == (gen + 1u) * nloc) {
;             __builtin_amdgcn_fence(__ATOMIC_RELEASE, "agent");
;             asm volatile("s_waitcnt vmcnt(0)" ::: "memory");
;             const unsigned og = xb_add(&bar[XB_TOP], 1u);
;             const unsigned tg = og / nx;
;             if (og + 1u == (tg + 1u) * nx) xb_add(&bar[XB_TOPGEN], 1u);
;             else XB_SPIN(xb_ld(&bar[XB_TOPGEN]) == tg, bar);
;             __builtin_amdgcn_fence(__ATOMIC_ACQUIRE, "agent");
;             xb_add(&bar[XB_XGEN(b.x)], 1u);
;             asm volatile("s_waitcnt vmcnt(0)" ::: "memory");
.LBB0_988:
	s_or_b64 exec, exec, s[6:7]
	v_cvt_f32_u32_e32 v4, v1
	s_waitcnt vmcnt(0)
	v_readfirstlane_b32 s2, v3
	s_mov_b64 s[8:9], 0
	v_rcp_iflag_f32_e32 v4, v4
	v_add_u32_e32 v2, s2, v2
	v_add_u32_e32 v5, 1, v2
	v_readlane_b32 s2, v244, 24
	v_mul_f32_e32 v3, 0x4f7ffffe, v4
	v_cvt_u32_f32_e32 v3, v3
	v_sub_u32_e32 v4, 0, v1
	v_readlane_b32 s3, v244, 25
	s_add_u32 s6, s2, 0x7500
	v_mul_lo_u32 v4, v4, v3
	v_mul_hi_u32 v4, v3, v4
	v_add_u32_e32 v3, v3, v4
	v_mul_hi_u32 v3, v2, v3
	v_mul_lo_u32 v4, v3, v1
	v_sub_u32_e32 v2, v2, v4
	v_add_u32_e32 v6, 1, v3
	v_cmp_ge_u32_e32 vcc, v2, v1
	v_sub_u32_e32 v4, v2, v1
	s_addc_u32 s7, s3, 0
	v_cndmask_b32_e32 v3, v3, v6, vcc
	v_cndmask_b32_e32 v2, v2, v4, vcc
	v_add_u32_e32 v4, 1, v3
	v_cmp_ge_u32_e32 vcc, v2, v1
	s_nop 1
	v_cndmask_b32_e32 v4, v3, v4, vcc
	v_mul_lo_u32 v2, v1, v4
	v_add_u32_e32 v1, v2, v1
	v_mov_b32_e32 v253, v1
	v_cmp_ne_u32_e32 vcc, v5, v1
	v_mov_b64_e32 v[2:3], s[6:7]
	s_and_saveexec_b64 s[2:3], vcc
	s_cbranch_execz .LBB0_1000
	v_mov_b32_e32 v1, 0
	global_load_dword v2, v1, s[6:7] offset:-256 sc1
	s_mov_b64 s[12:13], 0
	s_waitcnt vmcnt(0)
	v_cmp_lt_u32_e32 vcc, v2, v253
	s_and_saveexec_b64 s[10:11], vcc
	s_cbranch_execz .LBB0_999
	v_readlane_b32 s8, v244, 24
	v_readlane_b32 s9, v244, 25
	s_add_u32 s8, s8, 0x4200
	s_addc_u32 s9, s9, 0
	s_mov_b32 s22, 1
	s_branch .LBB0_992

; __device__ __forceinline__ unsigned xb_ld(unsigned* p)              { return __hip_atomic_load(p, __ATOMIC_RELAXED, __HIP_MEMORY_SCOPE_AGENT); }
; __device__ __forceinline__ unsigned xb_add(unsigned* p, unsigned v) { return __hip_atomic_fetch_add(p, v, __ATOMIC_RELAXED, __HIP_MEMORY_SCOPE_AGENT); }
; #define XB_SPIN(cond, bar) do { unsigned _sp = 0; while (cond) { __builtin_amdgcn_s_sleep(1); \
;     if ((++_sp & 255u) == 0u) { if (xb_ld(&(bar)[XB_TMO])) break; if (_sp > XB_SPIN_CAP) { atomicAdd(&(bar)[XB_TMO], 1u); break; } } } } while (0)
; __device__ __forceinline__ void xcd_barrier(const XcdBarrier& b) {
;     ...
;         const unsigned old = xb_add(&bar[XB_XSUB(b.x)], 1u);
;         const unsigned gen = old / nloc;
;         if (old + 1u == (gen + 1u) * nloc) {
;             __builtin_amdgcn_fence(__ATOMIC_RELEASE, "agent");
;             asm volatile("s_waitcnt vmcnt(0)" ::: "memory");
;             const unsigned og = xb_add(&bar[XB_TOP], 1u);
;             const unsigned tg = og / nx;
;             if (og + 1u == (tg + 1u) * nx) xb_add(&bar[XB_TOPGEN], 1u);
;             else XB_SPIN(xb_ld(&bar[XB_TOPGEN]) == tg, bar);
;             __builtin_amdgcn_fence(__ATOMIC_ACQUIRE, "agent");
;             xb_add(&bar[XB_XGEN(b.x)], 1u);
;             asm volatile("s_waitcnt vmcnt(0)" ::: "memory");
.LBB0_1112:
	s_or_b64 exec, exec, s[6:7]
	v_cvt_f32_u32_e32 v5, v2
	s_waitcnt vmcnt(0)
	v_readfirstlane_b32 s2, v4
	s_mov_b64 s[8:9], 0
	v_rcp_iflag_f32_e32 v5, v5
	v_add_u32_e32 v3, s2, v3
	v_add_u32_e32 v6, 1, v3
	v_readlane_b32 s2, v244, 24
	v_mul_f32_e32 v4, 0x4f7ffffe, v5
	v_cvt_u32_f32_e32 v4, v4
	v_sub_u32_e32 v5, 0, v2
	v_readlane_b32 s3, v244, 25
	s_add_u32 s6, s2, 0x7500
	v_mul_lo_u32 v5, v5, v4
	v_mul_hi_u32 v5, v4, v5
	v_add_u32_e32 v4, v4, v5
	v_mul_hi_u32 v4, v3, v4
	v_mul_lo_u32 v5, v4, v2
	v_sub_u32_e32 v3, v3, v5
	v_add_u32_e32 v7, 1, v4
	v_cmp_ge_u32_e32 vcc, v3, v2
	v_sub_u32_e32 v5, v3, v2
	s_addc_u32 s7, s3, 0
	v_cndmask_b32_e32 v4, v4, v7, vcc
	v_cndmask_b32_e32 v3, v3, v5, vcc
	v_add_u32_e32 v5, 1, v4
	v_cmp_ge_u32_e32 vcc, v3, v2
	s_nop 1
	v_cndmask_b32_e32 v4, v4, v5, vcc
	v_mul_lo_u32 v3, v2, v4
	v_add_u32_e32 v2, v3, v2
	v_mov_b32_e32 v253, v2
	v_cmp_ne_u32_e32 vcc, v6, v2
	v_mov_b64_e32 v[2:3], s[6:7]
	s_and_saveexec_b64 s[2:3], vcc
	s_cbranch_execz .LBB0_1124
	v_mov_b32_e32 v2, 0
	global_load_dword v3, v2, s[6:7] offset:-256 sc1
	s_mov_b64 s[12:13], 0
	s_waitcnt vmcnt(0)
	v_cmp_lt_u32_e32 vcc, v3, v253
	s_and_saveexec_b64 s[10:11], vcc
	s_cbranch_execz .LBB0_1123
	v_readlane_b32 s8, v244, 24
	v_readlane_b32 s9, v244, 25
	s_add_u32 s8, s8, 0x4200
	s_addc_u32 s9, s9, 0
	s_mov_b32 s22, 1
	s_branch .LBB0_1116

; __device__ __forceinline__ unsigned xb_ld(unsigned* p)              { return __hip_atomic_load(p, __ATOMIC_RELAXED, __HIP_MEMORY_SCOPE_AGENT); }
; __device__ __forceinline__ unsigned xb_add(unsigned* p, unsigned v) { return __hip_atomic_fetch_add(p, v, __ATOMIC_RELAXED, __HIP_MEMORY_SCOPE_AGENT); }
; #define XB_SPIN(cond, bar) do { unsigned _sp = 0; while (cond) { __builtin_amdgcn_s_sleep(1); \
;     if ((++_sp & 255u) == 0u) { if (xb_ld(&(bar)[XB_TMO])) break; if (_sp > XB_SPIN_CAP) { atomicAdd(&(bar)[XB_TMO], 1u); break; } } } } while (0)
; __device__ __forceinline__ void xcd_barrier(const XcdBarrier& b) {
;     ...
;         const unsigned old = xb_add(&bar[XB_XSUB(b.x)], 1u);
;         const unsigned gen = old / nloc;
;         if (old + 1u == (gen + 1u) * nloc) {
;             __builtin_amdgcn_fence(__ATOMIC_RELEASE, "agent");
;             asm volatile("s_waitcnt vmcnt(0)" ::: "memory");
;             const unsigned og = xb_add(&bar[XB_TOP], 1u);
;             const unsigned tg = og / nx;
;             if (og + 1u == (tg + 1u) * nx) xb_add(&bar[XB_TOPGEN], 1u);
;             else XB_SPIN(xb_ld(&bar[XB_TOPGEN]) == tg, bar);
;             __builtin_amdgcn_fence(__ATOMIC_ACQUIRE, "agent");
;             xb_add(&bar[XB_XGEN(b.x)], 1u);
;             asm volatile("s_waitcnt vmcnt(0)" ::: "memory");
.LBB0_1456:
	s_or_b64 exec, exec, s[6:7]
	v_cvt_f32_u32_e32 v5, v2
	s_waitcnt vmcnt(0)
	v_readfirstlane_b32 s2, v4
	s_add_u32 s6, s54, 0x7500
	s_addc_u32 s7, s55, 0
	v_rcp_iflag_f32_e32 v5, v5
	v_add_u32_e32 v3, s2, v3
	v_add_u32_e32 v6, 1, v3
	s_mov_b64 s[8:9], 0
	v_mul_f32_e32 v4, 0x4f7ffffe, v5
	v_cvt_u32_f32_e32 v4, v4
	v_sub_u32_e32 v5, 0, v2
	v_mul_lo_u32 v5, v5, v4
	v_mul_hi_u32 v5, v4, v5
	v_add_u32_e32 v4, v4, v5
	v_mul_hi_u32 v4, v3, v4
	v_mul_lo_u32 v5, v4, v2
	v_sub_u32_e32 v3, v3, v5
	v_add_u32_e32 v7, 1, v4
	v_cmp_ge_u32_e32 vcc, v3, v2
	v_sub_u32_e32 v5, v3, v2
	s_nop 0
	v_cndmask_b32_e32 v4, v4, v7, vcc
	v_cndmask_b32_e32 v3, v3, v5, vcc
	v_add_u32_e32 v5, 1, v4
	v_cmp_ge_u32_e32 vcc, v3, v2
	s_nop 1
	v_cndmask_b32_e32 v4, v4, v5, vcc
	v_mul_lo_u32 v3, v2, v4
	v_add_u32_e32 v2, v3, v2
	v_mov_b32_e32 v253, v2
	v_cmp_ne_u32_e32 vcc, v6, v2
	v_mov_b64_e32 v[2:3], s[6:7]
	s_and_saveexec_b64 s[2:3], vcc
	s_cbranch_execz .LBB0_1468
	v_mov_b32_e32 v2, 0
	global_load_dword v3, v2, s[6:7] offset:-256 sc1
	s_mov_b64 s[12:13], 0
	s_waitcnt vmcnt(0)
	v_cmp_lt_u32_e32 vcc, v3, v253
	s_and_saveexec_b64 s[10:11], vcc
	s_cbranch_execz .LBB0_1467
	s_add_u32 s8, s54, 0x4200
	s_addc_u32 s9, s55, 0
	s_mov_b32 s22, 1
	s_branch .LBB0_1460

; __device__ __forceinline__ unsigned xb_ld(unsigned* p)              { return __hip_atomic_load(p, __ATOMIC_RELAXED, __HIP_MEMORY_SCOPE_AGENT); }
; __device__ __forceinline__ unsigned xb_add(unsigned* p, unsigned v) { return __hip_atomic_fetch_add(p, v, __ATOMIC_RELAXED, __HIP_MEMORY_SCOPE_AGENT); }
; #define XB_SPIN(cond, bar) do { unsigned _sp = 0; while (cond) { __builtin_amdgcn_s_sleep(1); \
;     if ((++_sp & 255u) == 0u) { if (xb_ld(&(bar)[XB_TMO])) break; if (_sp > XB_SPIN_CAP) { atomicAdd(&(bar)[XB_TMO], 1u); break; } } } } while (0)
; __device__ __forceinline__ void xcd_barrier(const XcdBarrier& b) {
;     ...
;         const unsigned old = xb_add(&bar[XB_XSUB(b.x)], 1u);
;         const unsigned gen = old / nloc;
;         if (old + 1u == (gen + 1u) * nloc) {
;             __builtin_amdgcn_fence(__ATOMIC_RELEASE, "agent");
;             asm volatile("s_waitcnt vmcnt(0)" ::: "memory");
;             const unsigned og = xb_add(&bar[XB_TOP], 1u);
;             const unsigned tg = og / nx;
;             if (og + 1u == (tg + 1u) * nx) xb_add(&bar[XB_TOPGEN], 1u);
;             else XB_SPIN(xb_ld(&bar[XB_TOPGEN]) == tg, bar);
;             __builtin_amdgcn_fence(__ATOMIC_ACQUIRE, "agent");
;             xb_add(&bar[XB_XGEN(b.x)], 1u);
;             asm volatile("s_waitcnt vmcnt(0)" ::: "memory");
.LBB0_1594:
	s_or_b64 exec, exec, s[12:13]
	v_cvt_f32_u32_e32 v5, v2
	s_waitcnt vmcnt(0)
	v_readfirstlane_b32 s2, v4
	s_add_u32 s12, s54, 0x7500
	s_addc_u32 s13, s55, 0
	v_rcp_iflag_f32_e32 v5, v5
	v_add_u32_e32 v3, s2, v3
	v_add_u32_e32 v6, 1, v3
	s_mov_b64 s[14:15], 0
	v_mul_f32_e32 v4, 0x4f7ffffe, v5
	v_cvt_u32_f32_e32 v4, v4
	v_sub_u32_e32 v5, 0, v2
	v_mul_lo_u32 v5, v5, v4
	v_mul_hi_u32 v5, v4, v5
	v_add_u32_e32 v4, v4, v5
	v_mul_hi_u32 v4, v3, v4
	v_mul_lo_u32 v5, v4, v2
	v_sub_u32_e32 v3, v3, v5
	v_add_u32_e32 v7, 1, v4
	v_cmp_ge_u32_e32 vcc, v3, v2
	v_sub_u32_e32 v5, v3, v2
	s_nop 0
	v_cndmask_b32_e32 v4, v4, v7, vcc
	v_cndmask_b32_e32 v3, v3, v5, vcc
	v_add_u32_e32 v5, 1, v4
	v_cmp_ge_u32_e32 vcc, v3, v2
	s_nop 1
	v_cndmask_b32_e32 v4, v4, v5, vcc
	v_mul_lo_u32 v3, v2, v4
	v_add_u32_e32 v2, v3, v2
	v_mov_b32_e32 v253, v2
	v_cmp_ne_u32_e32 vcc, v6, v2
	v_mov_b64_e32 v[2:3], s[12:13]
	s_and_saveexec_b64 s[2:3], vcc
	s_cbranch_execz .LBB0_1606
	v_mov_b32_e32 v2, 0
	global_load_dword v3, v2, s[12:13] offset:-256 sc1
	s_mov_b64 s[18:19], 0
	s_waitcnt vmcnt(0)
	v_cmp_lt_u32_e32 vcc, v3, v253
	s_and_saveexec_b64 s[16:17], vcc
	s_cbranch_execz .LBB0_1605
	s_add_u32 s14, s54, 0x4200
	s_addc_u32 s15, s55, 0
	s_mov_b32 s28, 1
	s_branch .LBB0_1598
